# weight-transpose items (P0, P4): convert/store tail issues all 16 scratch reads first, counted waits (was one full LDS wait per read)
# speedup vs baseline: 1.0033x; 1.0033x over previous
.LBB0_54:
	ds_write_b32 v93, v19
	s_waitcnt lgkmcnt(0)
	s_waitcnt vmcnt(0)
	ds_read2_b32 v[126:127], v62 offset0:0 offset1:33
	ds_read2_b32 v[128:129], v62 offset0:66 offset1:99
	ds_read2_b32 v[130:131], v62 offset0:132 offset1:165
	ds_read2_b32 v[132:133], v62 offset0:198 offset1:231
	ds_read2_b32 v[134:135], v62 offset0:8 offset1:41
	ds_read2_b32 v[136:137], v62 offset0:74 offset1:107
	ds_read2_b32 v[138:139], v62 offset0:140 offset1:173
	ds_read2_b32 v[140:141], v62 offset0:206 offset1:239
	ds_read2_b32 v[142:143], v62 offset0:16 offset1:49
	ds_read2_b32 v[144:145], v62 offset0:82 offset1:115
	ds_read2_b32 v[146:147], v62 offset0:148 offset1:181
	ds_read2_b32 v[148:149], v62 offset0:214 offset1:247
	ds_read2_b32 v[150:151], v62 offset0:24 offset1:57
	ds_read2_b32 v[152:153], v62 offset0:90 offset1:123
	ds_read2_b32 v[154:155], v62 offset0:156 offset1:189
	ds_read2_b32 v[156:157], v62 offset0:222 offset1:255
	v_add3_u32 v6, v61, v64, v6
	v_lshl_add_u64 v[108:109], v[16:17], 1, v[14:15]
	v_add_u32_e32 v100, 0xe00, v6
	v_ashrrev_i32_e32 v101, 31, v100
	v_lshlrev_b64 v[100:101], 11, v[100:101]
	v_lshl_add_u64 v[100:101], v[108:109], 0, v[100:101]
	v_add_u32_e32 v102, 0xe08, v6
	v_ashrrev_i32_e32 v103, 31, v102
	v_lshlrev_b64 v[102:103], 11, v[102:103]
	v_lshl_add_u64 v[102:103], v[108:109], 0, v[102:103]
	v_add_u32_e32 v104, 0xe10, v6
	v_ashrrev_i32_e32 v105, 31, v104
	v_lshlrev_b64 v[104:105], 11, v[104:105]
	v_lshl_add_u64 v[104:105], v[108:109], 0, v[104:105]
	v_add_u32_e32 v106, 0xe18, v6
	v_ashrrev_i32_e32 v107, 31, v106
	v_lshlrev_b64 v[106:107], 11, v[106:107]
	v_lshl_add_u64 v[106:107], v[108:109], 0, v[106:107]
	s_waitcnt lgkmcnt(12)
	v_cvt_pk_bf16_f32 v110, v126, v127
	v_cvt_pk_bf16_f32 v111, v128, v129
	v_cvt_pk_bf16_f32 v112, v130, v131
	v_cvt_pk_bf16_f32 v113, v132, v133
	global_store_dwordx4 v[100:101], v[110:113], off
	s_waitcnt lgkmcnt(8)
	v_cvt_pk_bf16_f32 v114, v134, v135
	v_cvt_pk_bf16_f32 v115, v136, v137
	v_cvt_pk_bf16_f32 v116, v138, v139
	v_cvt_pk_bf16_f32 v117, v140, v141
	global_store_dwordx4 v[102:103], v[114:117], off
	s_waitcnt lgkmcnt(4)
	v_cvt_pk_bf16_f32 v118, v142, v143
	v_cvt_pk_bf16_f32 v119, v144, v145
	v_cvt_pk_bf16_f32 v120, v146, v147
	v_cvt_pk_bf16_f32 v121, v148, v149
	global_store_dwordx4 v[104:105], v[118:121], off
	s_waitcnt lgkmcnt(0)
	v_cvt_pk_bf16_f32 v122, v150, v151
	v_cvt_pk_bf16_f32 v123, v152, v153
	v_cvt_pk_bf16_f32 v124, v154, v155
	v_cvt_pk_bf16_f32 v125, v156, v157
	global_store_dwordx4 v[106:107], v[122:125], off
	s_waitcnt lgkmcnt(0)

.LBB0_875:
	ds_write_b32 v79, v13
	s_waitcnt lgkmcnt(0)
	s_waitcnt vmcnt(0)
	ds_read2_b32 v[116:117], v81 offset0:0 offset1:33
	ds_read2_b32 v[118:119], v81 offset0:66 offset1:99
	ds_read2_b32 v[120:121], v81 offset0:132 offset1:165
	ds_read2_b32 v[122:123], v81 offset0:198 offset1:231
	ds_read2_b32 v[124:125], v81 offset0:8 offset1:41
	ds_read2_b32 v[126:127], v81 offset0:74 offset1:107
	ds_read2_b32 v[128:129], v81 offset0:140 offset1:173
	ds_read2_b32 v[130:131], v81 offset0:206 offset1:239
	ds_read2_b32 v[132:133], v81 offset0:16 offset1:49
	ds_read2_b32 v[134:135], v81 offset0:82 offset1:115
	ds_read2_b32 v[136:137], v81 offset0:148 offset1:181
	ds_read2_b32 v[138:139], v81 offset0:214 offset1:247
	ds_read2_b32 v[140:141], v81 offset0:24 offset1:57
	ds_read2_b32 v[142:143], v81 offset0:90 offset1:123
	ds_read2_b32 v[144:145], v81 offset0:156 offset1:189
	ds_read2_b32 v[146:147], v81 offset0:222 offset1:255
	v_add3_u32 v2, v80, v85, v2
	v_lshl_add_u64 v[156:157], v[10:11], 1, v[6:7]
	v_add_u32_e32 v148, 0x16000, v2
	v_ashrrev_i32_e32 v149, 31, v148
	v_lshlrev_b64 v[148:149], 11, v[148:149]
	v_lshl_add_u64 v[148:149], v[156:157], 0, v[148:149]
	v_add_u32_e32 v150, 0x16008, v2
	v_ashrrev_i32_e32 v151, 31, v150
	v_lshlrev_b64 v[150:151], 11, v[150:151]
	v_lshl_add_u64 v[150:151], v[156:157], 0, v[150:151]
	v_add_u32_e32 v152, 0x16010, v2
	v_ashrrev_i32_e32 v153, 31, v152
	v_lshlrev_b64 v[152:153], 11, v[152:153]
	v_lshl_add_u64 v[152:153], v[156:157], 0, v[152:153]
	v_add_u32_e32 v154, 0x16018, v2
	v_ashrrev_i32_e32 v155, 31, v154
	v_lshlrev_b64 v[154:155], 11, v[154:155]
	v_lshl_add_u64 v[154:155], v[156:157], 0, v[154:155]
	s_waitcnt lgkmcnt(12)
	v_cvt_pk_bf16_f32 v158, v116, v117
	v_cvt_pk_bf16_f32 v159, v118, v119
	v_cvt_pk_bf16_f32 v160, v120, v121
	v_cvt_pk_bf16_f32 v161, v122, v123
	global_store_dwordx4 v[148:149], v[158:161], off
	s_waitcnt lgkmcnt(8)
	v_cvt_pk_bf16_f32 v162, v124, v125
	v_cvt_pk_bf16_f32 v163, v126, v127
	v_cvt_pk_bf16_f32 v164, v128, v129
	v_cvt_pk_bf16_f32 v165, v130, v131
	global_store_dwordx4 v[150:151], v[162:165], off
	s_waitcnt lgkmcnt(4)
	v_cvt_pk_bf16_f32 v166, v132, v133
	v_cvt_pk_bf16_f32 v167, v134, v135
	v_cvt_pk_bf16_f32 v168, v136, v137
	v_cvt_pk_bf16_f32 v169, v138, v139
	global_store_dwordx4 v[152:153], v[166:169], off
	s_waitcnt lgkmcnt(0)
	v_cvt_pk_bf16_f32 v170, v140, v141
	v_cvt_pk_bf16_f32 v171, v142, v143
	v_cvt_pk_bf16_f32 v172, v144, v145
	v_cvt_pk_bf16_f32 v173, v146, v147
	global_store_dwordx4 v[154:155], v[170:173], off
	s_waitcnt lgkmcnt(0)
